# P2 step 4 (U/W tiles) hand-scheduled: all fragments read up front (transposed image fragments shared by both tiles), one MFMA chain per tile, no accumulator copies
# speedup vs baseline: 1.0110x; 1.0110x over previous
.LBB0_334:
	s_nop 3
	v_lshlrev_b32_e32 v0, 8, v44
	v_mov_b32_e32 v1, v132
	v_lshl_add_u64 v[0:1], v[40:41], 0, v[0:1]
	v_lshl_add_u64 v[2:3], v[42:43], 0, 64
	v_cndmask_b32_e64 v1, v1, v3, s[0:1]
	v_cndmask_b32_e64 v0, v0, v2, s[0:1]
	v_cvt_pk_bf16_f32 v2, v228, v229
	v_cvt_pk_bf16_f32 v3, v230, v231
	global_store_dwordx2 v[0:1], v[2:3], off
	v_cvt_pk_bf16_f32 v2, v232, v233
	v_cvt_pk_bf16_f32 v3, v234, v235
	global_store_dwordx2 v[0:1], v[2:3], off offset:16
	v_cvt_pk_bf16_f32 v2, v236, v237
	v_cvt_pk_bf16_f32 v3, v238, v239
	global_store_dwordx2 v[0:1], v[2:3], off offset:32
	v_cvt_pk_bf16_f32 v2, v240, v241
	v_cvt_pk_bf16_f32 v3, v242, v243
	s_andn2_b64 vcc, exec, s[48:49]
	global_store_dwordx2 v[0:1], v[2:3], off offset:48
	s_waitcnt lgkmcnt(0)
	s_barrier
	s_cbranch_vccz .LBB0_437

.LBB0_405:
	s_cmp_gt_u32 s14, 3
	s_cselect_b64 s[42:43], -1, 0
	s_cmp_lt_u32 s14, 4
	s_cselect_b64 s[0:1], -1, 0
	s_and_b64 vcc, s[0:1], exec
	s_cselect_b32 s4, s62, 0xcc00
	s_add_i32 s4, s4, 0
	s_and_b32 s14, s3, 0x60
	v_lshlrev_b32_e32 v1, 4, v26
	v_lshlrev_b32_e32 v2, 2, v25
	v_mov_b32_e32 v0, s4
	v_or3_b32 v1, v1, v2, s14
	v_mad_i32_i24 v0, v30, s57, v0
	v_lshlrev_b32_e32 v1, 1, v1
	v_add_u32_e32 v140, v0, v1
	v_add_u32_e32 v141, s59, v24
	s_waitcnt lgkmcnt(0)
	s_barrier
	v_mad_u32_u24 v226, v134, s61, v141
	v_or_b32_e32 v44, 32, v176
	v_mad_u32_u24 v227, v44, s61, v141
	ds_read_b64_tr_b16 v[178:179], v140
	ds_read_b64_tr_b16 v[180:181], v140 offset:1088
	ds_read_b128 v[194:197], v226
	ds_read_b64_tr_b16 v[182:183], v140 offset:4352
	ds_read_b64_tr_b16 v[184:185], v140 offset:5440
	ds_read_b128 v[198:201], v226 offset:32
	ds_read_b64_tr_b16 v[186:187], v140 offset:8704
	ds_read_b64_tr_b16 v[188:189], v140 offset:9792
	ds_read_b128 v[202:205], v226 offset:64
	ds_read_b64_tr_b16 v[190:191], v140 offset:13056
	ds_read_b64_tr_b16 v[192:193], v140 offset:14144
	ds_read_b128 v[206:209], v226 offset:96
	ds_read_b128 v[210:213], v227
	ds_read_b128 v[214:217], v227 offset:32
	ds_read_b128 v[218:221], v227 offset:64
	s_and_b64 vcc, exec, s[0:1]
	s_cbranch_vccnz .Ls4_u
	s_waitcnt lgkmcnt(12)
	v_mfma_f32_32x32x16_bf16 v[0:15], v[178:181], v[194:197], 0
	ds_read_b128 v[222:225], v227 offset:96
	s_waitcnt lgkmcnt(10)
	v_mfma_f32_32x32x16_bf16 v[0:15], v[182:185], v[198:201], v[0:15]
	s_waitcnt lgkmcnt(7)
	v_mfma_f32_32x32x16_bf16 v[0:15], v[186:189], v[202:205], v[0:15]
	s_waitcnt lgkmcnt(4)
	v_mfma_f32_32x32x16_bf16 v[0:15], v[190:193], v[206:209], v[0:15]
	s_waitcnt lgkmcnt(3)
	v_mfma_f32_32x32x16_bf16 v[228:243], v[178:181], v[210:213], 0
	s_waitcnt lgkmcnt(2)
	v_mfma_f32_32x32x16_bf16 v[228:243], v[182:185], v[214:217], v[228:243]
	s_waitcnt lgkmcnt(1)
	v_mfma_f32_32x32x16_bf16 v[228:243], v[186:189], v[218:221], v[228:243]
	s_waitcnt lgkmcnt(0)
	v_mfma_f32_32x32x16_bf16 v[228:243], v[190:193], v[222:225], v[228:243]
	s_branch .Ls4_epi
.Ls4_u:
	s_waitcnt lgkmcnt(12)
	v_mfma_f32_32x32x16_bf16 v[0:15], v[194:197], v[178:181], 0
	ds_read_b128 v[222:225], v227 offset:96
	s_waitcnt lgkmcnt(10)
	v_mfma_f32_32x32x16_bf16 v[0:15], v[198:201], v[182:185], v[0:15]
	s_waitcnt lgkmcnt(7)
	v_mfma_f32_32x32x16_bf16 v[0:15], v[202:205], v[186:189], v[0:15]
	s_waitcnt lgkmcnt(4)
	v_mfma_f32_32x32x16_bf16 v[0:15], v[206:209], v[190:193], v[0:15]
	s_waitcnt lgkmcnt(3)
	v_mfma_f32_32x32x16_bf16 v[228:243], v[210:213], v[178:181], 0
	s_waitcnt lgkmcnt(2)
	v_mfma_f32_32x32x16_bf16 v[228:243], v[214:217], v[182:185], v[228:243]
	s_waitcnt lgkmcnt(1)
	v_mfma_f32_32x32x16_bf16 v[228:243], v[218:221], v[186:189], v[228:243]
	s_waitcnt lgkmcnt(0)
	v_mfma_f32_32x32x16_bf16 v[228:243], v[222:225], v[190:193], v[228:243]
.Ls4_epi:
	s_lshl_b64 s[40:41], s[40:41], 14
	s_add_u32 s33, s72, s40
	s_addc_u32 s43, s73, s41
	s_lshl_b32 s14, s14, 1
	s_add_u32 s42, s33, s14
	s_addc_u32 s43, s43, 0
	s_add_u32 s40, s28, s40
	v_or_b32_e32 v18, s3, v134
	s_addc_u32 s41, s29, s41
	v_lshlrev_b32_e32 v18, 7, v18
	v_mov_b32_e32 v19, v132
	v_lshlrev_b32_e32 v16, 1, v135
	v_mov_b32_e32 v17, v132
	v_lshl_add_u64 v[18:19], s[40:41], 0, v[18:19]
	v_lshl_add_u64 v[40:41], s[42:43], 0, v[16:17]
	v_lshl_add_u64 v[42:43], v[18:19], 0, v[16:17]
	v_lshlrev_b32_e32 v16, 8, v134
	v_lshl_add_u64 v[16:17], v[40:41], 0, v[16:17]
	v_cndmask_b32_e64 v25, v17, v43, s[0:1]
	v_cndmask_b32_e64 v24, v16, v42, s[0:1]
	v_cvt_pk_bf16_f32 v0, v0, v1
	v_cvt_pk_bf16_f32 v1, v2, v3
	global_store_dwordx2 v[24:25], v[0:1], off
	v_cvt_pk_bf16_f32 v0, v4, v5
	v_cvt_pk_bf16_f32 v1, v6, v7
	global_store_dwordx2 v[24:25], v[0:1], off offset:16
	v_cvt_pk_bf16_f32 v0, v8, v9
	v_cvt_pk_bf16_f32 v1, v10, v11
	global_store_dwordx2 v[24:25], v[0:1], off offset:32
	v_cvt_pk_bf16_f32 v0, v12, v13
	v_cvt_pk_bf16_f32 v1, v14, v15
	global_store_dwordx2 v[24:25], v[0:1], off offset:48
	s_branch .LBB0_334
